# v18 + trailing half's per-tile barrier moved from after P.V to after the NEXT tile's QK^T MFMAs (runs ahead by one QK block; first loop tile skips it, exit path adds one)
# speedup vs baseline: 1.0062x; 1.0037x over previous
.LqT_rest:
	v_add_u32_e32 v116, s54, v214
	v_add_u32_e32 v216, v116, v157
	v_add_u32_e32 v218, v116, v208
	v_add_u32_e32 v217, v116, v193
	v_add_u32_e32 v219, v116, v209
	v_mfma_f32_32x32x16_bf16 v[64:79], v[136:139], v[104:107], v[64:79]
	v_mfma_f32_32x32x16_bf16 v[80:95], v[120:123], v[104:107], v[80:95]
	v_mfma_f32_32x32x16_bf16 v[64:79], v[140:143], v[100:103], v[64:79]
	v_mfma_f32_32x32x16_bf16 v[80:95], v[124:127], v[100:103], v[80:95]
	v_mfma_f32_32x32x16_bf16 v[80:95], v[112:115], v[96:99], v[80:95]
	ds_read_b128 v[242:245], v216 offset:16384
	ds_read_b128 v[246:249], v216 offset:20480
	ds_read_b128 v[250:253], v216 offset:24576
	ds_read_b128 v[200:203], v216 offset:28672
	ds_read_b128 v[220:223], v217 offset:16384
	ds_read_b128 v[224:227], v217 offset:20480
	ds_read_b128 v[234:237], v217 offset:24576
	ds_read_b128 v[238:241], v217 offset:28672
	v_mfma_f32_32x32x16_bf16 v[64:79], v[128:131], v[96:99], v[64:79]
	s_cmp_eq_u32 s33, 0
	s_cbranch_scc1 .LqT_xt
	s_barrier
.LqT_xt:
	s_nop 11
	v_max_f32_e32 v128, v65, v65
	v_max_f32_e32 v129, v64, v64
	v_max_f32_e32 v128, v129, v128
	v_max3_f32 v129, v66, v67, v81
	v_max3_f32 v128, v128, v80, v82
	v_max3_f32 v128, v128, v83, v68
	v_max3_f32 v129, v129, v70, v71
	v_max3_f32 v128, v128, v69, v84
	v_max3_f32 v129, v129, v86, v87
	v_max3_f32 v128, v128, v85, v72
	v_max3_f32 v129, v129, v74, v75
	v_max3_f32 v128, v128, v73, v88
	v_max3_f32 v129, v129, v90, v91
	v_max3_f32 v128, v128, v89, v76
	v_max3_f32 v129, v129, v78, v79
	v_max3_f32 v128, v128, v77, v92
	v_max3_f32 v129, v129, v94, v95
	v_max3_f32 v128, v128, v93, v129
	v_cmp_lt_f32_e32 vcc, s88, v128
	s_cbranch_vccnz .LqT_rescale
.LqT_g0:
	v_exp_f32_e32 v64, v64
	v_exp_f32_e32 v65, v65
	v_exp_f32_e32 v66, v66
	v_exp_f32_e32 v67, v67
	v_add_f32_e32 v184, v64, v65
	v_exp_f32_e32 v68, v68
	v_exp_f32_e32 v69, v69
	v_cvt_pk_bf16_f32 v64, v64, v65
	v_add_f32_e32 v185, v66, v67
	v_cvt_pk_bf16_f32 v65, v66, v67
	v_exp_f32_e32 v70, v70
	v_exp_f32_e32 v71, v71
	v_add_f32_e32 v186, v68, v69
	v_cvt_pk_bf16_f32 v66, v68, v69
	v_add_f32_e32 v184, v184, v185
	v_add_f32_e32 v187, v70, v71
	v_cvt_pk_bf16_f32 v67, v70, v71
	v_add_f32_e32 v186, v186, v187
	v_add_f32_e32 v184, v184, v186
	v_add_f32_e32 v206, v206, v184
	s_waitcnt vmcnt(0) lgkmcnt(0)
	s_add_i32 s54, s33, 1
	s_setprio 1
	v_mfma_f32_32x32x16_bf16 v[32:47], v[242:245], v[64:67], v[32:47]
	v_exp_f32_e32 v72, v72
	v_exp_f32_e32 v73, v73
	v_exp_f32_e32 v74, v74
	v_exp_f32_e32 v75, v75
	v_add_f32_e32 v184, v72, v73
	s_and_b32 s100, s65, 0x18000
	v_add_u32_e32 v194, s100, v149
	v_add_u32_e32 v195, v194, v157
	v_add_u32_e32 v196, v194, v193
	ds_read_b128 v[242:245], v218 offset:16384
	v_mfma_f32_32x32x16_bf16 v[48:63], v[246:249], v[64:67], v[48:63]
	v_exp_f32_e32 v76, v76
	v_exp_f32_e32 v77, v77
	v_cvt_pk_bf16_f32 v68, v72, v73
	v_add_f32_e32 v185, v74, v75
	v_cvt_pk_bf16_f32 v69, v74, v75
	v_add_u32_e32 v197, v194, v208
	v_add_u32_e32 v194, v194, v209
	ds_read_b128 v[132:135], v195
	ds_read_b128 v[116:119], v195 offset:4096
	ds_read_b128 v[246:249], v218 offset:20480
	v_mfma_f32_32x32x16_bf16 v[16:31], v[250:253], v[64:67], v[16:31]
	v_exp_f32_e32 v78, v78
	v_exp_f32_e32 v79, v79
	v_add_f32_e32 v186, v76, v77
	v_cvt_pk_bf16_f32 v70, v76, v77
	v_add_f32_e32 v184, v184, v185
	ds_read_b128 v[136:139], v196
	ds_read_b128 v[120:123], v196 offset:4096
	ds_read_b128 v[140:143], v197
	ds_read_b128 v[124:127], v197 offset:4096
	ds_read_b128 v[250:253], v218 offset:24576
	v_mfma_f32_32x32x16_bf16 v[0:15], v[200:203], v[64:67], v[0:15]
	v_add_f32_e32 v187, v78, v79
	v_cvt_pk_bf16_f32 v71, v78, v79
	v_add_f32_e32 v186, v186, v187
	v_add_f32_e32 v184, v184, v186
	v_add_f32_e32 v206, v206, v184
	ds_read_b128 v[128:131], v194
	ds_read_b128 v[112:115], v194 offset:4096
	ds_read_b128 v[200:203], v218 offset:28672
	v_mfma_f32_32x32x16_bf16 v[32:47], v[220:223], v[68:71], v[32:47]
	v_exp_f32_e32 v80, v80
	v_exp_f32_e32 v81, v81
	v_exp_f32_e32 v82, v82
	v_exp_f32_e32 v83, v83
	v_add_f32_e32 v184, v80, v81
	ds_read_b128 v[220:223], v219 offset:16384
	v_mfma_f32_32x32x16_bf16 v[48:63], v[224:227], v[68:71], v[48:63]
	v_exp_f32_e32 v84, v84
	v_exp_f32_e32 v85, v85
	v_cvt_pk_bf16_f32 v72, v80, v81
	v_add_f32_e32 v185, v82, v83
	v_cvt_pk_bf16_f32 v73, v82, v83
	ds_read_b128 v[224:227], v219 offset:20480
	v_mfma_f32_32x32x16_bf16 v[16:31], v[234:237], v[68:71], v[16:31]
	v_exp_f32_e32 v86, v86
	v_exp_f32_e32 v87, v87
	v_add_f32_e32 v186, v84, v85
	v_cvt_pk_bf16_f32 v74, v84, v85
	v_add_f32_e32 v184, v184, v185
	ds_read_b128 v[234:237], v219 offset:24576
	v_mfma_f32_32x32x16_bf16 v[0:15], v[238:241], v[68:71], v[0:15]
	v_add_f32_e32 v187, v86, v87
	v_cvt_pk_bf16_f32 v75, v86, v87
	v_add_f32_e32 v186, v186, v187
	v_add_f32_e32 v184, v184, v186
	v_add_f32_e32 v206, v206, v184
	ds_read_b128 v[238:241], v219 offset:28672
	s_waitcnt lgkmcnt(4)
	v_mfma_f32_32x32x16_bf16 v[32:47], v[242:245], v[72:75], v[32:47]
	v_exp_f32_e32 v88, v88
	v_exp_f32_e32 v89, v89
	v_exp_f32_e32 v90, v90
	v_exp_f32_e32 v91, v91
	v_add_f32_e32 v184, v88, v89
	v_mfma_f32_32x32x16_bf16 v[48:63], v[246:249], v[72:75], v[48:63]
	v_exp_f32_e32 v92, v92
	v_exp_f32_e32 v93, v93
	v_cvt_pk_bf16_f32 v76, v88, v89
	v_add_f32_e32 v185, v90, v91
	v_cvt_pk_bf16_f32 v77, v90, v91
	v_mfma_f32_32x32x16_bf16 v[16:31], v[250:253], v[72:75], v[16:31]
	v_exp_f32_e32 v94, v94
	v_exp_f32_e32 v95, v95
	v_add_f32_e32 v186, v92, v93
	v_cvt_pk_bf16_f32 v78, v92, v93
	v_add_f32_e32 v184, v184, v185
	v_mfma_f32_32x32x16_bf16 v[0:15], v[200:203], v[72:75], v[0:15]
	v_add_f32_e32 v187, v94, v95
	v_cvt_pk_bf16_f32 v79, v94, v95
	v_add_f32_e32 v186, v186, v187
	v_add_f32_e32 v184, v184, v186
	v_add_f32_e32 v206, v206, v184
	s_waitcnt lgkmcnt(0)
	v_mfma_f32_32x32x16_bf16 v[32:47], v[220:223], v[76:79], v[32:47]
	v_mfma_f32_32x32x16_bf16 v[48:63], v[224:227], v[76:79], v[48:63]
	s_waitcnt lgkmcnt(0)
	s_add_i32 s65, s65, 0x8000
	s_addk_i32 s23, 0x100
	s_add_i32 s36, s36, 64
	s_mov_b32 s33, s54
	s_cmpk_eq_i32 s23, 0x1e00
	v_mfma_f32_32x32x16_bf16 v[16:31], v[234:237], v[76:79], v[16:31]
	v_mfma_f32_32x32x16_bf16 v[0:15], v[238:241], v[76:79], v[0:15]
	s_setprio 0
	s_cbranch_scc0 .LqT_top
	s_barrier
	s_branch .LBB0_284

.LqT_rescale:
	s_mov_b32 s98, 0
	ds_bpermute_b32 v129, v210, v128
	s_waitcnt lgkmcnt(0)
	v_max_f32_e32 v129, v129, v129
	v_max_f32_e32 v128, v128, v129
	v_cmp_lt_f32_e32 vcc, s88, v128
	s_nop 0
	s_nop 0
	v_cndmask_b32_e32 v128, 0, v128, vcc
	v_exp_f32_e64 v130, -v128
	v_pk_add_f32 v[64:65], v[64:65], v[128:129] op_sel_hi:[1,0] neg_lo:[0,1] neg_hi:[0,1]
	v_pk_add_f32 v[80:81], v[80:81], v[128:129] op_sel_hi:[1,0] neg_lo:[0,1] neg_hi:[0,1]
	v_pk_add_f32 v[66:67], v[66:67], v[128:129] op_sel_hi:[1,0] neg_lo:[0,1] neg_hi:[0,1]
	v_pk_mul_f32 v[46:47], v[46:47], v[130:131] op_sel_hi:[1,0]
	v_pk_mul_f32 v[44:45], v[44:45], v[130:131] op_sel_hi:[1,0]
	v_pk_mul_f32 v[42:43], v[42:43], v[130:131] op_sel_hi:[1,0]
	v_pk_mul_f32 v[40:41], v[40:41], v[130:131] op_sel_hi:[1,0]
	v_pk_mul_f32 v[38:39], v[38:39], v[130:131] op_sel_hi:[1,0]
	v_pk_mul_f32 v[36:37], v[36:37], v[130:131] op_sel_hi:[1,0]
	v_pk_mul_f32 v[34:35], v[34:35], v[130:131] op_sel_hi:[1,0]
	v_pk_mul_f32 v[32:33], v[32:33], v[130:131] op_sel_hi:[1,0]
	v_pk_mul_f32 v[62:63], v[62:63], v[130:131] op_sel_hi:[1,0]
	v_pk_mul_f32 v[60:61], v[60:61], v[130:131] op_sel_hi:[1,0]
	v_pk_mul_f32 v[58:59], v[58:59], v[130:131] op_sel_hi:[1,0]
	v_pk_mul_f32 v[56:57], v[56:57], v[130:131] op_sel_hi:[1,0]
	v_pk_mul_f32 v[54:55], v[54:55], v[130:131] op_sel_hi:[1,0]
	v_pk_mul_f32 v[52:53], v[52:53], v[130:131] op_sel_hi:[1,0]
	v_pk_mul_f32 v[50:51], v[50:51], v[130:131] op_sel_hi:[1,0]
	v_pk_mul_f32 v[48:49], v[48:49], v[130:131] op_sel_hi:[1,0]
	v_pk_mul_f32 v[30:31], v[30:31], v[130:131] op_sel_hi:[1,0]
	v_pk_mul_f32 v[28:29], v[28:29], v[130:131] op_sel_hi:[1,0]
	v_pk_mul_f32 v[26:27], v[26:27], v[130:131] op_sel_hi:[1,0]
	v_pk_mul_f32 v[24:25], v[24:25], v[130:131] op_sel_hi:[1,0]
	v_pk_mul_f32 v[22:23], v[22:23], v[130:131] op_sel_hi:[1,0]
	v_pk_mul_f32 v[20:21], v[20:21], v[130:131] op_sel_hi:[1,0]
	v_pk_mul_f32 v[18:19], v[18:19], v[130:131] op_sel_hi:[1,0]
	v_pk_mul_f32 v[16:17], v[16:17], v[130:131] op_sel_hi:[1,0]
	v_pk_mul_f32 v[14:15], v[14:15], v[130:131] op_sel_hi:[1,0]
	v_pk_mul_f32 v[12:13], v[12:13], v[130:131] op_sel_hi:[1,0]
	v_pk_mul_f32 v[10:11], v[10:11], v[130:131] op_sel_hi:[1,0]
	v_pk_mul_f32 v[8:9], v[8:9], v[130:131] op_sel_hi:[1,0]
	v_pk_mul_f32 v[6:7], v[6:7], v[130:131] op_sel_hi:[1,0]
	v_pk_mul_f32 v[4:5], v[4:5], v[130:131] op_sel_hi:[1,0]
	v_pk_mul_f32 v[2:3], v[2:3], v[130:131] op_sel_hi:[1,0]
	v_pk_mul_f32 v[0:1], v[0:1], v[130:131] op_sel_hi:[1,0]
	v_mov_b32_e32 v131, v128
	v_pk_add_f32 v[82:83], v[82:83], v[128:129] op_sel_hi:[1,0] neg_lo:[0,1] neg_hi:[0,1]
	v_pk_add_f32 v[68:69], v[68:69], v[128:129] op_sel_hi:[1,0] neg_lo:[0,1] neg_hi:[0,1]
	v_pk_add_f32 v[84:85], v[84:85], v[128:129] op_sel_hi:[1,0] neg_lo:[0,1] neg_hi:[0,1]
	v_pk_add_f32 v[70:71], v[70:71], v[128:129] op_sel_hi:[1,0] neg_lo:[0,1] neg_hi:[0,1]
	v_pk_add_f32 v[86:87], v[86:87], v[128:129] op_sel_hi:[1,0] neg_lo:[0,1] neg_hi:[0,1]
	v_pk_add_f32 v[72:73], v[72:73], v[128:129] op_sel_hi:[1,0] neg_lo:[0,1] neg_hi:[0,1]
	v_pk_add_f32 v[88:89], v[88:89], v[128:129] op_sel_hi:[1,0] neg_lo:[0,1] neg_hi:[0,1]
	v_pk_add_f32 v[74:75], v[74:75], v[128:129] op_sel_hi:[1,0] neg_lo:[0,1] neg_hi:[0,1]
	v_pk_add_f32 v[90:91], v[90:91], v[128:129] op_sel_hi:[1,0] neg_lo:[0,1] neg_hi:[0,1]
	v_pk_add_f32 v[76:77], v[76:77], v[128:129] op_sel_hi:[1,0] neg_lo:[0,1] neg_hi:[0,1]
	v_pk_add_f32 v[92:93], v[92:93], v[128:129] op_sel_hi:[1,0] neg_lo:[0,1] neg_hi:[0,1]
	v_pk_add_f32 v[78:79], v[78:79], v[128:129] op_sel_hi:[1,0] neg_lo:[0,1] neg_hi:[0,1]
	v_pk_add_f32 v[94:95], v[94:95], v[128:129] op_sel_hi:[1,0] neg_lo:[0,1] neg_hi:[0,1]
	v_pk_add_f32 v[128:129], v[206:207], v[130:131]
	v_pk_mul_f32 v[206:207], v[206:207], v[130:131]
	s_nop 0
	v_mov_b32_e32 v207, v129
	s_branch .LqT_g0
	s_nop 0
	s_nop 0
	s_nop 0
	s_nop 0
	s_nop 0
	s_nop 0
	s_nop 0
	s_nop 0
	s_nop 0
	s_nop 0
	s_nop 0
	s_nop 0
	s_nop 0
	s_nop 0
	s_nop 0
